# baseline (speedup 1.0000x reference)
; __device__ __forceinline__ int gdim() { int g = gridDim.x; asm volatile("" : "+s"(g)); return g; }
; #define SK_LOAD(KK) do { rb = *(const uint4*)(bp + (KK)); \
;     if constexpr (AF32) { fa[0] = *(const float4*)(fp0 + (KK)); fa[1] = *(const float4*)(fp0 + (KK) + 4); \
;                           fa[2] = *(const float4*)(fp1 + (KK)); fa[3] = *(const float4*)(fp1 + (KK) + 4); } \
;     else { ra0 = *(const uint4*)(ap0 + (KK)); ra1 = *(const uint4*)(ap1 + (KK)); } } while (0)
; template <bool AF32>
; __device__ __forceinline__ void skinny_gemm(const void* __restrict__ Av, long lda, const u16* __restrict__ Bt, long ldb, int kb, int ke,
;                                             f32x4* acc, char* smem, int tid) {
;     ...
;   SK_LOAD(kb);
;   for (int k0 = kb; k0 < ke; k0 += 64) {
;     if constexpr (AF32) {
;       float f0[8] = {fa[0].x, fa[0].y, fa[0].z, fa[0].w, fa[1].x, fa[1].y, fa[1].z, fa[1].w};
;       float f1[8] = {fa[2].x, fa[2].y, fa[2].z, fa[2].w, fa[3].x, fa[3].y, fa[3].z, fa[3].w};
;       ra0 = pack8(f0); ra1 = pack8(f1);
;     }
;     *(uint4*)(As + r0 * 72 + v0 * 8) = ra0;
;     *(uint4*)(As + (r0 + 64) * 72 + v0 * 8) = ra1;
;     *(uint4*)(Bs + r0 * 72 + v0 * 8) = rb;
;     __syncthreads();
;     if (k0 + 64 < ke) SK_LOAD(k0 + 64);
; #pragma unroll
;     for (int ks = 0; ks < 2; ++ks) {
;       const bf16x8 af = *(const bf16x8*)(As + (wid * 16 + fr) * 72 + ks * 32 + fq * 8);
; #pragma unroll
;       for (int nb = 0; nb < 4; ++nb) {
;         const bf16x8 bf = *(const bf16x8*)(Bs + (nb * 16 + fr) * 72 + ks * 32 + fq * 8);
;         acc[nb] = __builtin_amdgcn_mfma_f32_16x16x32_bf16(af, bf, acc[nb], 0, 0, 0);
;       }
;     }
;     __syncthreads();
;   }
; __global__ void __launch_bounds__(512) mega(Params Pk) {
;     ...
;       for (int task = pb; task < 192; task += gdim()) {
;         const int tk = task & 31, br = (task >> 5) % 3, ksp = task / 96;
;         const u16* Ab = (br == 0) ? ASSM : (br == 1 ? ASC : AATT);
;         const u16* Wb = (br == 0) ? WssmT : (br == 1 ? WscT : WattT);
;         f32x4 acc[4] = {};
;         skinny_gemm<false>(Ab + (long)NP * D, D, Wb + (long)tk * 64 * D, D, ksp * 1024, ksp * 1024 + 1024, acc, smem, tid_);
.LBB0_1096:
	s_ashr_i32 s6, s0, 5
	s_mul_hi_i32 s7, s6, 0x55555556
	s_lshr_b32 s8, s7, 31
	s_add_i32 s7, s7, s8
	s_mul_i32 s7, s7, 3
	s_sub_i32 s10, s6, s7
	s_mul_hi_i32 s6, s0, 0x2aaaaaab
	s_lshr_b32 s7, s6, 31
	s_lshr_b32 s6, s6, 4
	s_and_b32 s1, s0, 31
	s_add_i32 s6, s6, s7
	s_cmp_eq_u32 s10, 1
	v_readlane_b32 s7, v251, 32
	v_readlane_b32 s8, v251, 34
	s_cselect_b32 s7, s7, s8
	v_readlane_b32 s8, v251, 33
	v_readlane_b32 s9, v251, 35
	s_cselect_b32 s8, s8, s9
	v_readlane_b32 s9, v251, 40
	v_readlane_b32 s11, v251, 42
	s_cselect_b32 s9, s9, s11
	v_readlane_b32 s11, v251, 41
	v_readlane_b32 s12, v251, 43
	s_cselect_b32 s11, s11, s12
	s_cmp_eq_u32 s10, 0
	v_readlane_b32 s12, v251, 29
	s_cselect_b32 s13, s12, s8
	v_readlane_b32 s8, v251, 24
	s_cselect_b32 s12, s8, s7
	v_readlane_b32 s7, v251, 39
	v_readlane_b32 s8, v251, 38
	s_cselect_b32 s7, s7, s11
	s_cselect_b32 s11, s8, s9
	s_add_u32 s8, s12, 0x2000000
	s_addc_u32 s9, s13, 0
	s_lshl_b32 s14, s1, 18
	s_add_u32 s14, s11, s14
	s_addc_u32 s15, s7, 0
	s_lshl_b32 s6, s6, 10
	v_lshl_add_u64 v[8:9], s[14:15], 0, v[64:65]
	v_lshl_add_u64 v[66:67], v[8:9], 0, v[2:3]
	v_lshl_add_u64 v[8:9], s[8:9], 0, v[64:65]
	v_lshl_add_u64 v[10:11], s[8:9], 0, v[0:1]
	s_ashr_i32 s7, s6, 31
	v_lshl_add_u64 v[8:9], v[8:9], 0, v[2:3]
	v_lshl_add_u64 v[10:11], v[10:11], 0, v[2:3]
	s_lshl_b64 s[8:9], s[6:7], 1
	v_lshl_add_u64 v[10:11], v[10:11], 0, s[8:9]
	v_lshl_add_u64 v[8:9], v[8:9], 0, s[8:9]
	v_mov_b64_e32 v[194:195], v[10:11]
	v_mov_b64_e32 v[192:193], v[8:9]
	global_load_dwordx4 v[32:35], v[10:11], off
	global_load_dwordx4 v[28:31], v[8:9], off
	v_lshl_add_u64 v[8:9], v[66:67], 0, s[8:9]
	v_mov_b64_e32 v[196:197], v[8:9]
	global_load_dwordx4 v[24:27], v[8:9], off
	v_mov_b32_e32 v20, 0
	s_or_b32 s7, s6, 0x3c0
	v_lshl_add_u64 v[68:69], s[12:13], 0, v[62:63]
	v_mov_b32_e32 v21, v20
	v_mov_b32_e32 v22, v20
	v_mov_b32_e32 v23, v20
	v_mov_b32_e32 v16, v20
	v_mov_b32_e32 v17, v20
	v_mov_b32_e32 v18, v20
	v_mov_b32_e32 v19, v20
	v_mov_b32_e32 v12, v20
	v_mov_b32_e32 v13, v20
	v_mov_b32_e32 v14, v20
	v_mov_b32_e32 v15, v20
	v_mov_b32_e32 v8, v20
	v_mov_b32_e32 v9, v20
	v_mov_b32_e32 v10, v20
	v_mov_b32_e32 v11, v20
	v_mov_b32_e32 v198, 0x80
	v_mov_b32_e32 v199, 0
	s_mov_b32 s11, 0
	v_lshl_add_u64 v[194:195], v[194:195], 0, v[198:199]
	v_lshl_add_u64 v[192:193], v[192:193], 0, v[198:199]
	v_lshl_add_u64 v[196:197], v[196:197], 0, v[198:199]
	global_load_dwordx4 v[94:97], v[194:195], off
	global_load_dwordx4 v[90:93], v[192:193], off
	global_load_dwordx4 v[98:101], v[196:197], off
	v_lshl_add_u64 v[194:195], v[194:195], 0, v[198:199]
	v_lshl_add_u64 v[192:193], v[192:193], 0, v[198:199]
	v_lshl_add_u64 v[196:197], v[196:197], 0, v[198:199]
	global_load_dwordx4 v[106:109], v[194:195], off
	global_load_dwordx4 v[102:105], v[192:193], off
	global_load_dwordx4 v[110:113], v[196:197], off
.Lsk7_loop:
	v_lshl_add_u64 v[194:195], v[194:195], 0, v[198:199]
	v_lshl_add_u64 v[192:193], v[192:193], 0, v[198:199]
	v_lshl_add_u64 v[196:197], v[196:197], 0, v[198:199]
	global_load_dwordx4 v[118:121], v[194:195], off
	global_load_dwordx4 v[114:117], v[192:193], off
	global_load_dwordx4 v[122:125], v[196:197], off
	s_waitcnt vmcnt(9)
	ds_write_b128 v75, v[28:31]
	ds_write_b128 v37, v[32:35]
	ds_write_b128 v75, v[24:27] offset:18432
	s_waitcnt lgkmcnt(0)
	s_barrier
	ds_read_b128 v[208:211], v36
	ds_read_b128 v[216:219], v76 offset:18432
	ds_read_b128 v[220:223], v76 offset:20736
	ds_read_b128 v[234:237], v76 offset:23040
	ds_read_b128 v[238:241], v76 offset:25344
	ds_read_b128 v[212:215], v36 offset:64
	ds_read_b128 v[242:245], v76 offset:18496
	ds_read_b128 v[246:249], v76 offset:20800
	ds_read_b128 v[200:203], v76 offset:23104
	ds_read_b128 v[204:207], v76 offset:25408
	s_waitcnt lgkmcnt(8)
	v_mfma_f32_16x16x32_bf16 v[20:23], v[208:211], v[216:219], v[20:23]
	s_waitcnt lgkmcnt(7)
	v_mfma_f32_16x16x32_bf16 v[16:19], v[208:211], v[220:223], v[16:19]
	s_waitcnt lgkmcnt(6)
	v_mfma_f32_16x16x32_bf16 v[12:15], v[208:211], v[234:237], v[12:15]
	s_waitcnt lgkmcnt(5)
	v_mfma_f32_16x16x32_bf16 v[8:11], v[208:211], v[238:241], v[8:11]
	s_waitcnt lgkmcnt(3)
	v_mfma_f32_16x16x32_bf16 v[20:23], v[212:215], v[242:245], v[20:23]
	s_waitcnt lgkmcnt(2)
	v_mfma_f32_16x16x32_bf16 v[16:19], v[212:215], v[246:249], v[16:19]
	s_waitcnt lgkmcnt(1)
	v_mfma_f32_16x16x32_bf16 v[12:15], v[212:215], v[200:203], v[12:15]
	s_waitcnt lgkmcnt(0)
	s_barrier
	v_mfma_f32_16x16x32_bf16 v[8:11], v[212:215], v[204:207], v[8:11]
	v_lshl_add_u64 v[194:195], v[194:195], 0, v[198:199]
	v_lshl_add_u64 v[192:193], v[192:193], 0, v[198:199]
	v_lshl_add_u64 v[196:197], v[196:197], 0, v[198:199]
	global_load_dwordx4 v[32:35], v[194:195], off
	global_load_dwordx4 v[28:31], v[192:193], off
	global_load_dwordx4 v[24:27], v[196:197], off
	s_waitcnt vmcnt(9)
	ds_write_b128 v75, v[90:93]
	ds_write_b128 v37, v[94:97]
	ds_write_b128 v75, v[98:101] offset:18432
	s_waitcnt lgkmcnt(0)
	s_barrier
	ds_read_b128 v[208:211], v36
	ds_read_b128 v[216:219], v76 offset:18432
	ds_read_b128 v[220:223], v76 offset:20736
	ds_read_b128 v[234:237], v76 offset:23040
	ds_read_b128 v[238:241], v76 offset:25344
	ds_read_b128 v[212:215], v36 offset:64
	ds_read_b128 v[242:245], v76 offset:18496
	ds_read_b128 v[246:249], v76 offset:20800
	ds_read_b128 v[200:203], v76 offset:23104
	ds_read_b128 v[204:207], v76 offset:25408
	s_waitcnt lgkmcnt(8)
	v_mfma_f32_16x16x32_bf16 v[20:23], v[208:211], v[216:219], v[20:23]
	s_waitcnt lgkmcnt(7)
	v_mfma_f32_16x16x32_bf16 v[16:19], v[208:211], v[220:223], v[16:19]
	s_waitcnt lgkmcnt(6)
	v_mfma_f32_16x16x32_bf16 v[12:15], v[208:211], v[234:237], v[12:15]
	s_waitcnt lgkmcnt(5)
	v_mfma_f32_16x16x32_bf16 v[8:11], v[208:211], v[238:241], v[8:11]
	s_waitcnt lgkmcnt(3)
	v_mfma_f32_16x16x32_bf16 v[20:23], v[212:215], v[242:245], v[20:23]
	s_waitcnt lgkmcnt(2)
	v_mfma_f32_16x16x32_bf16 v[16:19], v[212:215], v[246:249], v[16:19]
	s_waitcnt lgkmcnt(1)
	v_mfma_f32_16x16x32_bf16 v[12:15], v[212:215], v[200:203], v[12:15]
	s_waitcnt lgkmcnt(0)
	s_barrier
; #define SK_LOAD(KK) do { rb = *(const uint4*)(bp + (KK)); \
;     if constexpr (AF32) { fa[0] = *(const float4*)(fp0 + (KK)); fa[1] = *(const float4*)(fp0 + (KK) + 4); \
;                           fa[2] = *(const float4*)(fp1 + (KK)); fa[3] = *(const float4*)(fp1 + (KK) + 4); } \
;     else { ra0 = *(const uint4*)(ap0 + (KK)); ra1 = *(const uint4*)(ap1 + (KK)); } } while (0)
; template <bool AF32>
; __device__ __forceinline__ void skinny_gemm(const void* __restrict__ Av, long lda, const u16* __restrict__ Bt, long ldb, int kb, int ke,
;                                             f32x4* acc, char* smem, int tid) {
;     ...
;   for (int k0 = kb; k0 < ke; k0 += 64) {
;     if constexpr (AF32) {
;       float f0[8] = {fa[0].x, fa[0].y, fa[0].z, fa[0].w, fa[1].x, fa[1].y, fa[1].z, fa[1].w};
;       float f1[8] = {fa[2].x, fa[2].y, fa[2].z, fa[2].w, fa[3].x, fa[3].y, fa[3].z, fa[3].w};
;       ra0 = pack8(f0); ra1 = pack8(f1);
;     }
;     *(uint4*)(As + r0 * 72 + v0 * 8) = ra0;
;     *(uint4*)(As + (r0 + 64) * 72 + v0 * 8) = ra1;
;     *(uint4*)(Bs + r0 * 72 + v0 * 8) = rb;
;     __syncthreads();
;     if (k0 + 64 < ke) SK_LOAD(k0 + 64);
; #pragma unroll
;     for (int ks = 0; ks < 2; ++ks) {
;       const bf16x8 af = *(const bf16x8*)(As + (wid * 16 + fr) * 72 + ks * 32 + fq * 8);
; #pragma unroll
;       for (int nb = 0; nb < 4; ++nb) {
;         const bf16x8 bf = *(const bf16x8*)(Bs + (nb * 16 + fr) * 72 + ks * 32 + fq * 8);
;         acc[nb] = __builtin_amdgcn_mfma_f32_16x16x32_bf16(af, bf, acc[nb], 0, 0, 0);
;       }
;     }
;     __syncthreads();
;   }
	v_mfma_f32_16x16x32_bf16 v[8:11], v[212:215], v[204:207], v[8:11]
	v_lshl_add_u64 v[194:195], v[194:195], 0, v[198:199]
	v_lshl_add_u64 v[192:193], v[192:193], 0, v[198:199]
	v_lshl_add_u64 v[196:197], v[196:197], 0, v[198:199]
	global_load_dwordx4 v[94:97], v[194:195], off
	global_load_dwordx4 v[90:93], v[192:193], off
	global_load_dwordx4 v[98:101], v[196:197], off
	s_waitcnt vmcnt(9)
	ds_write_b128 v75, v[102:105]
	ds_write_b128 v37, v[106:109]
	ds_write_b128 v75, v[110:113] offset:18432
	s_waitcnt lgkmcnt(0)
	s_barrier
	ds_read_b128 v[208:211], v36
	ds_read_b128 v[216:219], v76 offset:18432
	ds_read_b128 v[220:223], v76 offset:20736
	ds_read_b128 v[234:237], v76 offset:23040
	ds_read_b128 v[238:241], v76 offset:25344
	ds_read_b128 v[212:215], v36 offset:64
	ds_read_b128 v[242:245], v76 offset:18496
	ds_read_b128 v[246:249], v76 offset:20800
	ds_read_b128 v[200:203], v76 offset:23104
	ds_read_b128 v[204:207], v76 offset:25408
	s_waitcnt lgkmcnt(8)
	v_mfma_f32_16x16x32_bf16 v[20:23], v[208:211], v[216:219], v[20:23]
	s_waitcnt lgkmcnt(7)
	v_mfma_f32_16x16x32_bf16 v[16:19], v[208:211], v[220:223], v[16:19]
	s_waitcnt lgkmcnt(6)
	v_mfma_f32_16x16x32_bf16 v[12:15], v[208:211], v[234:237], v[12:15]
	s_waitcnt lgkmcnt(5)
	v_mfma_f32_16x16x32_bf16 v[8:11], v[208:211], v[238:241], v[8:11]
	s_waitcnt lgkmcnt(3)
	v_mfma_f32_16x16x32_bf16 v[20:23], v[212:215], v[242:245], v[20:23]
	s_waitcnt lgkmcnt(2)
	v_mfma_f32_16x16x32_bf16 v[16:19], v[212:215], v[246:249], v[16:19]
	s_waitcnt lgkmcnt(1)
	v_mfma_f32_16x16x32_bf16 v[12:15], v[212:215], v[200:203], v[12:15]
	s_waitcnt lgkmcnt(0)
	s_barrier
	v_mfma_f32_16x16x32_bf16 v[8:11], v[212:215], v[204:207], v[8:11]
	v_lshl_add_u64 v[194:195], v[194:195], 0, v[198:199]
	v_lshl_add_u64 v[192:193], v[192:193], 0, v[198:199]
	v_lshl_add_u64 v[196:197], v[196:197], 0, v[198:199]
	global_load_dwordx4 v[106:109], v[194:195], off
	global_load_dwordx4 v[102:105], v[192:193], off
	global_load_dwordx4 v[110:113], v[196:197], off
	s_waitcnt vmcnt(9)
	ds_write_b128 v75, v[114:117]
	ds_write_b128 v37, v[118:121]
	ds_write_b128 v75, v[122:125] offset:18432
	s_waitcnt lgkmcnt(0)
	s_barrier
	ds_read_b128 v[208:211], v36
	ds_read_b128 v[216:219], v76 offset:18432
	ds_read_b128 v[220:223], v76 offset:20736
	ds_read_b128 v[234:237], v76 offset:23040
	ds_read_b128 v[238:241], v76 offset:25344
	ds_read_b128 v[212:215], v36 offset:64
	ds_read_b128 v[242:245], v76 offset:18496
	ds_read_b128 v[246:249], v76 offset:20800
	ds_read_b128 v[200:203], v76 offset:23104
	ds_read_b128 v[204:207], v76 offset:25408
	s_waitcnt lgkmcnt(8)
	v_mfma_f32_16x16x32_bf16 v[20:23], v[208:211], v[216:219], v[20:23]
	s_waitcnt lgkmcnt(7)
	v_mfma_f32_16x16x32_bf16 v[16:19], v[208:211], v[220:223], v[16:19]
	s_waitcnt lgkmcnt(6)
	v_mfma_f32_16x16x32_bf16 v[12:15], v[208:211], v[234:237], v[12:15]
	s_waitcnt lgkmcnt(5)
	v_mfma_f32_16x16x32_bf16 v[8:11], v[208:211], v[238:241], v[8:11]
	s_waitcnt lgkmcnt(3)
	v_mfma_f32_16x16x32_bf16 v[20:23], v[212:215], v[242:245], v[20:23]
	s_waitcnt lgkmcnt(2)
	v_mfma_f32_16x16x32_bf16 v[16:19], v[212:215], v[246:249], v[16:19]
	s_waitcnt lgkmcnt(1)
	v_mfma_f32_16x16x32_bf16 v[12:15], v[212:215], v[200:203], v[12:15]
	s_waitcnt lgkmcnt(0)
	s_barrier
	v_mfma_f32_16x16x32_bf16 v[8:11], v[212:215], v[204:207], v[8:11]
	s_add_i32 s11, s11, 4
	s_cmp_lt_u32 s11, 12
	s_cbranch_scc1 .Lsk7_loop
	v_lshl_add_u64 v[194:195], v[194:195], 0, v[198:199]
	v_lshl_add_u64 v[192:193], v[192:193], 0, v[198:199]
	v_lshl_add_u64 v[196:197], v[196:197], 0, v[198:199]
	global_load_dwordx4 v[118:121], v[194:195], off
	global_load_dwordx4 v[114:117], v[192:193], off
	global_load_dwordx4 v[122:125], v[196:197], off
	s_waitcnt vmcnt(9)
	ds_write_b128 v75, v[28:31]
	ds_write_b128 v37, v[32:35]
	ds_write_b128 v75, v[24:27] offset:18432
	s_waitcnt lgkmcnt(0)
	s_barrier
	ds_read_b128 v[208:211], v36
	ds_read_b128 v[216:219], v76 offset:18432
	ds_read_b128 v[220:223], v76 offset:20736
	ds_read_b128 v[234:237], v76 offset:23040
	ds_read_b128 v[238:241], v76 offset:25344
	ds_read_b128 v[212:215], v36 offset:64
	ds_read_b128 v[242:245], v76 offset:18496
	ds_read_b128 v[246:249], v76 offset:20800
	ds_read_b128 v[200:203], v76 offset:23104
	ds_read_b128 v[204:207], v76 offset:25408
	s_waitcnt lgkmcnt(8)
	v_mfma_f32_16x16x32_bf16 v[20:23], v[208:211], v[216:219], v[20:23]
	s_waitcnt lgkmcnt(7)
	v_mfma_f32_16x16x32_bf16 v[16:19], v[208:211], v[220:223], v[16:19]
	s_waitcnt lgkmcnt(6)
	v_mfma_f32_16x16x32_bf16 v[12:15], v[208:211], v[234:237], v[12:15]
	s_waitcnt lgkmcnt(5)
	v_mfma_f32_16x16x32_bf16 v[8:11], v[208:211], v[238:241], v[8:11]
	s_waitcnt lgkmcnt(3)
	v_mfma_f32_16x16x32_bf16 v[20:23], v[212:215], v[242:245], v[20:23]
	s_waitcnt lgkmcnt(2)
	v_mfma_f32_16x16x32_bf16 v[16:19], v[212:215], v[246:249], v[16:19]
	s_waitcnt lgkmcnt(1)
	v_mfma_f32_16x16x32_bf16 v[12:15], v[212:215], v[200:203], v[12:15]
	s_waitcnt lgkmcnt(0)
	s_barrier
; #define SK_LOAD(KK) do { rb = *(const uint4*)(bp + (KK)); \
;     if constexpr (AF32) { fa[0] = *(const float4*)(fp0 + (KK)); fa[1] = *(const float4*)(fp0 + (KK) + 4); \
;                           fa[2] = *(const float4*)(fp1 + (KK)); fa[3] = *(const float4*)(fp1 + (KK) + 4); } \
;     else { ra0 = *(const uint4*)(ap0 + (KK)); ra1 = *(const uint4*)(ap1 + (KK)); } } while (0)
; template <bool AF32>
; __device__ __forceinline__ void skinny_gemm(const void* __restrict__ Av, long lda, const u16* __restrict__ Bt, long ldb, int kb, int ke,
;                                             f32x4* acc, char* smem, int tid) {
;     ...
;   for (int k0 = kb; k0 < ke; k0 += 64) {
;     if constexpr (AF32) {
;       float f0[8] = {fa[0].x, fa[0].y, fa[0].z, fa[0].w, fa[1].x, fa[1].y, fa[1].z, fa[1].w};
;       float f1[8] = {fa[2].x, fa[2].y, fa[2].z, fa[2].w, fa[3].x, fa[3].y, fa[3].z, fa[3].w};
;       ra0 = pack8(f0); ra1 = pack8(f1);
;     }
;     *(uint4*)(As + r0 * 72 + v0 * 8) = ra0;
;     *(uint4*)(As + (r0 + 64) * 72 + v0 * 8) = ra1;
;     *(uint4*)(Bs + r0 * 72 + v0 * 8) = rb;
;     __syncthreads();
;     if (k0 + 64 < ke) SK_LOAD(k0 + 64);
; #pragma unroll
;     for (int ks = 0; ks < 2; ++ks) {
;       const bf16x8 af = *(const bf16x8*)(As + (wid * 16 + fr) * 72 + ks * 32 + fq * 8);
; #pragma unroll
;       for (int nb = 0; nb < 4; ++nb) {
;         const bf16x8 bf = *(const bf16x8*)(Bs + (nb * 16 + fr) * 72 + ks * 32 + fq * 8);
;         acc[nb] = __builtin_amdgcn_mfma_f32_16x16x32_bf16(af, bf, acc[nb], 0, 0, 0);
;       }
;     }
;     __syncthreads();
;   }
	v_mfma_f32_16x16x32_bf16 v[8:11], v[212:215], v[204:207], v[8:11]
	s_waitcnt vmcnt(6)
	ds_write_b128 v75, v[90:93]
	ds_write_b128 v37, v[94:97]
	ds_write_b128 v75, v[98:101] offset:18432
	s_waitcnt lgkmcnt(0)
	s_barrier
	ds_read_b128 v[208:211], v36
	ds_read_b128 v[216:219], v76 offset:18432
	ds_read_b128 v[220:223], v76 offset:20736
	ds_read_b128 v[234:237], v76 offset:23040
	ds_read_b128 v[238:241], v76 offset:25344
	ds_read_b128 v[212:215], v36 offset:64
	ds_read_b128 v[242:245], v76 offset:18496
	ds_read_b128 v[246:249], v76 offset:20800
	ds_read_b128 v[200:203], v76 offset:23104
	ds_read_b128 v[204:207], v76 offset:25408
	s_waitcnt lgkmcnt(8)
	v_mfma_f32_16x16x32_bf16 v[20:23], v[208:211], v[216:219], v[20:23]
	s_waitcnt lgkmcnt(7)
	v_mfma_f32_16x16x32_bf16 v[16:19], v[208:211], v[220:223], v[16:19]
	s_waitcnt lgkmcnt(6)
	v_mfma_f32_16x16x32_bf16 v[12:15], v[208:211], v[234:237], v[12:15]
	s_waitcnt lgkmcnt(5)
	v_mfma_f32_16x16x32_bf16 v[8:11], v[208:211], v[238:241], v[8:11]
	s_waitcnt lgkmcnt(3)
	v_mfma_f32_16x16x32_bf16 v[20:23], v[212:215], v[242:245], v[20:23]
	s_waitcnt lgkmcnt(2)
	v_mfma_f32_16x16x32_bf16 v[16:19], v[212:215], v[246:249], v[16:19]
	s_waitcnt lgkmcnt(1)
	v_mfma_f32_16x16x32_bf16 v[12:15], v[212:215], v[200:203], v[12:15]
	s_waitcnt lgkmcnt(0)
	s_barrier
	v_mfma_f32_16x16x32_bf16 v[8:11], v[212:215], v[204:207], v[8:11]
	s_waitcnt vmcnt(3)
	ds_write_b128 v75, v[102:105]
	ds_write_b128 v37, v[106:109]
	ds_write_b128 v75, v[110:113] offset:18432
	s_waitcnt lgkmcnt(0)
	s_barrier
	ds_read_b128 v[208:211], v36
	ds_read_b128 v[216:219], v76 offset:18432
	ds_read_b128 v[220:223], v76 offset:20736
	ds_read_b128 v[234:237], v76 offset:23040
	ds_read_b128 v[238:241], v76 offset:25344
	ds_read_b128 v[212:215], v36 offset:64
	ds_read_b128 v[242:245], v76 offset:18496
	ds_read_b128 v[246:249], v76 offset:20800
	ds_read_b128 v[200:203], v76 offset:23104
	ds_read_b128 v[204:207], v76 offset:25408
	s_waitcnt lgkmcnt(8)
	v_mfma_f32_16x16x32_bf16 v[20:23], v[208:211], v[216:219], v[20:23]
	s_waitcnt lgkmcnt(7)
	v_mfma_f32_16x16x32_bf16 v[16:19], v[208:211], v[220:223], v[16:19]
	s_waitcnt lgkmcnt(6)
	v_mfma_f32_16x16x32_bf16 v[12:15], v[208:211], v[234:237], v[12:15]
	s_waitcnt lgkmcnt(5)
	v_mfma_f32_16x16x32_bf16 v[8:11], v[208:211], v[238:241], v[8:11]
	s_waitcnt lgkmcnt(3)
	v_mfma_f32_16x16x32_bf16 v[20:23], v[212:215], v[242:245], v[20:23]
	s_waitcnt lgkmcnt(2)
	v_mfma_f32_16x16x32_bf16 v[16:19], v[212:215], v[246:249], v[16:19]
	s_waitcnt lgkmcnt(1)
	v_mfma_f32_16x16x32_bf16 v[12:15], v[212:215], v[200:203], v[12:15]
	s_waitcnt lgkmcnt(0)
	s_barrier
	v_mfma_f32_16x16x32_bf16 v[8:11], v[212:215], v[204:207], v[8:11]
	s_waitcnt vmcnt(0)
	ds_write_b128 v75, v[114:117]
	ds_write_b128 v37, v[118:121]
	ds_write_b128 v75, v[122:125] offset:18432
	s_waitcnt lgkmcnt(0)
	s_barrier
	ds_read_b128 v[208:211], v36
	ds_read_b128 v[216:219], v76 offset:18432
	ds_read_b128 v[220:223], v76 offset:20736
	ds_read_b128 v[234:237], v76 offset:23040
	ds_read_b128 v[238:241], v76 offset:25344
	ds_read_b128 v[212:215], v36 offset:64
	ds_read_b128 v[242:245], v76 offset:18496
	ds_read_b128 v[246:249], v76 offset:20800
	ds_read_b128 v[200:203], v76 offset:23104
	ds_read_b128 v[204:207], v76 offset:25408
	s_waitcnt lgkmcnt(8)
	v_mfma_f32_16x16x32_bf16 v[20:23], v[208:211], v[216:219], v[20:23]
	s_waitcnt lgkmcnt(7)
	v_mfma_f32_16x16x32_bf16 v[16:19], v[208:211], v[220:223], v[16:19]
	s_waitcnt lgkmcnt(6)
	v_mfma_f32_16x16x32_bf16 v[12:15], v[208:211], v[234:237], v[12:15]
	s_waitcnt lgkmcnt(5)
	v_mfma_f32_16x16x32_bf16 v[8:11], v[208:211], v[238:241], v[8:11]
	s_waitcnt lgkmcnt(3)
	v_mfma_f32_16x16x32_bf16 v[20:23], v[212:215], v[242:245], v[20:23]
	s_waitcnt lgkmcnt(2)
	v_mfma_f32_16x16x32_bf16 v[16:19], v[212:215], v[246:249], v[16:19]
	s_waitcnt lgkmcnt(1)
	v_mfma_f32_16x16x32_bf16 v[12:15], v[212:215], v[200:203], v[12:15]
	s_waitcnt lgkmcnt(0)
	s_barrier
	v_mfma_f32_16x16x32_bf16 v[8:11], v[212:215], v[204:207], v[8:11]
	s_branch .LBB0_1095
